# compressed-attention unit epilogue: gate and the four read-modify-write loads in flight together
# speedup vs baseline: 1.2470x; 1.0017x over previous
.LBB0_624:
	s_mul_i32 s0, s60, 3
	s_waitcnt lgkmcnt(0)
	v_lshlrev_b64 v[0:1], 7, v[64:65]
	s_ashr_i32 s1, s0, 31
	v_lshl_add_u64 v[0:1], s[24:25], 0, v[0:1]
	v_lshl_add_u64 v[0:1], s[0:1], 1, v[0:1]
	global_load_ushort v0, v[0:1], off
	v_mov_b32_e32 v87, v65
	v_mov_b64_e32 v[2:3], s[20:21]
	v_mad_u64_u32 v[2:3], s[0:1], v64, s94, v[2:3]
	v_lshl_add_u64 v[2:3], s[16:17], 1, v[2:3]
	v_lshl_add_u64 v[4:5], v[2:3], 0, v[86:87]
	s_mov_b64 s[0:1], 0x6d01000
	v_lshl_add_u64 v[16:17], v[4:5], 0, s[0:1]
	global_load_dwordx2 v[6:7], v[16:17], off offset:0
	global_load_dwordx2 v[10:11], v[16:17], off offset:32
	global_load_dwordx2 v[12:13], v[16:17], off offset:64
	global_load_dwordx2 v[14:15], v[16:17], off offset:96
	s_waitcnt vmcnt(4)
	v_lshlrev_b32_e32 v0, 16, v0
	v_mul_f32_e32 v0, 0xbfb8aa3b, v0
	v_exp_f32_e32 v0, v0
	s_nop 0
	v_add_f32_e32 v0, 1.0, v0
	v_div_scale_f32 v1, s[0:1], v0, v0, 1.0
	v_rcp_f32_e32 v2, v1
	s_nop 0
	v_fma_f32 v3, -v1, v2, 1.0
	v_fmac_f32_e32 v2, v3, v2
	v_div_scale_f32 v3, vcc, 1.0, v0, 1.0
	v_mul_f32_e32 v4, v3, v2
	v_fma_f32 v5, -v1, v4, v3
	v_fmac_f32_e32 v4, v5, v2
	v_fma_f32 v1, -v1, v4, v3
	v_div_fmas_f32 v1, v1, v2, v4
	v_div_fixup_f32 v0, v1, v0, 1.0
	s_waitcnt vmcnt(0)
	v_lshlrev_b32_e32 v8, 16, v6
	v_and_b32_e32 v9, 0xffff0000, v6
	v_pk_fma_f32 v[8:9], v[44:45], v[0:1], v[8:9] op_sel_hi:[1,0,1]
	v_lshlrev_b32_e32 v2, 16, v7
	v_and_b32_e32 v3, 0xffff0000, v7
	v_pk_fma_f32 v[2:3], v[46:47], v[0:1], v[2:3] op_sel_hi:[1,0,1]
	v_cvt_pk_bf16_f32 v6, v8, v9
	v_cvt_pk_bf16_f32 v7, v2, v3
	global_store_dwordx2 v[16:17], v[6:7], off offset:0
	v_lshlrev_b32_e32 v8, 16, v10
	v_and_b32_e32 v9, 0xffff0000, v10
	v_pk_fma_f32 v[8:9], v[40:41], v[0:1], v[8:9] op_sel_hi:[1,0,1]
	v_lshlrev_b32_e32 v2, 16, v11
	v_and_b32_e32 v3, 0xffff0000, v11
	v_pk_fma_f32 v[2:3], v[42:43], v[0:1], v[2:3] op_sel_hi:[1,0,1]
	v_cvt_pk_bf16_f32 v10, v8, v9
	v_cvt_pk_bf16_f32 v11, v2, v3
	global_store_dwordx2 v[16:17], v[10:11], off offset:32
	v_lshlrev_b32_e32 v8, 16, v12
	v_and_b32_e32 v9, 0xffff0000, v12
	v_pk_fma_f32 v[8:9], v[36:37], v[0:1], v[8:9] op_sel_hi:[1,0,1]
	v_lshlrev_b32_e32 v2, 16, v13
	v_and_b32_e32 v3, 0xffff0000, v13
	v_pk_fma_f32 v[2:3], v[38:39], v[0:1], v[2:3] op_sel_hi:[1,0,1]
	v_cvt_pk_bf16_f32 v12, v8, v9
	v_cvt_pk_bf16_f32 v13, v2, v3
	global_store_dwordx2 v[16:17], v[12:13], off offset:64
	v_lshlrev_b32_e32 v8, 16, v14
	v_and_b32_e32 v9, 0xffff0000, v14
	v_pk_fma_f32 v[8:9], v[32:33], v[0:1], v[8:9] op_sel_hi:[1,0,1]
	v_lshlrev_b32_e32 v2, 16, v15
	v_and_b32_e32 v3, 0xffff0000, v15
	v_pk_fma_f32 v[2:3], v[34:35], v[0:1], v[2:3] op_sel_hi:[1,0,1]
	v_cvt_pk_bf16_f32 v14, v8, v9
	v_cvt_pk_bf16_f32 v15, v2, v3
	global_store_dwordx2 v[16:17], v[14:15], off offset:96
